# gdn_prep KK^T/QK^T tile: twelve fragment loads batched with counted waits (on top of EpiR, attention tail and scan-loop edits)
# baseline (speedup 1.0000x reference)
; #define MFMA16(a, b, c) __builtin_amdgcn_mfma_f32_16x16x32_bf16((a), (b), (c), 0, 0, 0)
; template <int C> DI void gdn_prep_item(const Params& p, int l, int ci, int r0, int h, unsigned char* smem) {
;     ...
;     for (int id = w; id < NT * NT; id += 8) { const int ti = id / NT, tj = id % NT;
;         f32x4 akk = (f32x4){0.f, 0.f, 0.f, 0.f}, aqk = akk;
;         if (tj <= ti) {
; #pragma unroll
;             for (int s = 0; s < 4; ++s) { const size_t co = (size_t)h * 128 + 32 * s + 8 * gq;
;                 const bf16x8 ka = *(const bf16x8*)(QZ + (size_t)(r0 + 16 * ti + l15) * NQZ + 512 + co), qa = *(const bf16x8*)(QZ + (size_t)(r0 + 16 * ti + l15) * NQZ + co),
;                              kb = *(const bf16x8*)(QZ + (size_t)(r0 + 16 * tj + l15) * NQZ + 512 + co);
;                 akk = MFMA16(ka, kb, akk); aqk = MFMA16(qa, kb, aqk); } }
.LBB0_583:
	v_ashrrev_i32_e32 v0, 31, v13
	v_lshrrev_b32_e32 v0, 30, v0
	v_add_u32_e32 v0, v13, v0
	v_ashrrev_i32_e32 v27, 2, v0
	v_and_b32_e32 v0, -4, v0
	v_sub_u32_e32 v0, v13, v0
	v_cmp_le_i32_e32 vcc, v0, v27
	v_lshlrev_b32_e32 v0, 6, v27
	v_lshlrev_b32_e32 v18, 4, v27
	v_sub_u32_e32 v19, 0, v0
	s_and_saveexec_b64 s[4:5], vcc
	s_xor_b64 s[8:9], exec, s[4:5]
	s_cbranch_execz .LBB0_585
	v_add_u32_e32 v1, v23, v24
	v_add_u32_e32 v2, v18, v17
	v_sub_u32_e32 v19, 0, v0
	v_sub_u32_e32 v0, v1, v0
	v_ashrrev_i32_e32 v3, 31, v2
	v_ashrrev_i32_e32 v1, 31, v0
	v_lshlrev_b64 v[2:3], 12, v[2:3]
	v_lshlrev_b64 v[28:29], 12, v[0:1]
	v_lshl_add_u64 v[32:33], v[10:11], 0, v[2:3]
	v_lshl_add_u64 v[44:45], v[10:11], 0, v[28:29]
	global_load_dwordx4 v[70:73], v[32:33], off offset:1024
	global_load_dwordx4 v[86:89], v[32:33], off
	global_load_dwordx4 v[102:105], v[44:45], off offset:1024
	global_load_dwordx4 v[74:77], v[32:33], off offset:1088
	global_load_dwordx4 v[90:93], v[32:33], off offset:64
	global_load_dwordx4 v[106:109], v[44:45], off offset:1088
	global_load_dwordx4 v[78:81], v[32:33], off offset:1152
	global_load_dwordx4 v[94:97], v[32:33], off offset:128
	global_load_dwordx4 v[110:113], v[44:45], off offset:1152
	global_load_dwordx4 v[82:85], v[32:33], off offset:1216
	global_load_dwordx4 v[98:101], v[32:33], off offset:192
	global_load_dwordx4 v[114:117], v[44:45], off offset:1216
	s_waitcnt vmcnt(9)
	v_mfma_f32_16x16x32_bf16 v[4:7], v[70:73], v[102:105], 0
	v_mfma_f32_16x16x32_bf16 v[0:3], v[86:89], v[102:105], 0
	s_waitcnt vmcnt(6)
	v_mfma_f32_16x16x32_bf16 v[4:7], v[74:77], v[106:109], v[4:7]
	v_mfma_f32_16x16x32_bf16 v[0:3], v[90:93], v[106:109], v[0:3]
	s_waitcnt vmcnt(3)
	v_mfma_f32_16x16x32_bf16 v[4:7], v[78:81], v[110:113], v[4:7]
	v_mfma_f32_16x16x32_bf16 v[0:3], v[94:97], v[110:113], v[0:3]
	s_waitcnt vmcnt(0)
	v_mfma_f32_16x16x32_bf16 v[4:7], v[82:85], v[114:117], v[4:7]
	v_mfma_f32_16x16x32_bf16 v[0:3], v[98:101], v[114:117], v[0:3]
